# conv_mla: two conv_matrix instances loaded their 32 gain values one at a time (load-wait each); now issued together
# baseline (speedup 1.0000x reference)
.LBB0_915:
	v_mul_hi_i32 v2, v21, s81
	v_lshrrev_b32_e32 v3, 31, v2
	v_ashrrev_i32_e32 v2, 3, v2
	v_add_u32_e32 v2, v2, v3
	v_lshlrev_b32_e32 v4, 6, v2
	v_mad_u64_u32 v[2:3], s[0:1], v2, s49, v[12:13]
	v_or_b32_e32 v14, v4, v13
	v_mov_b64_e32 v[16:17], s[16:17]
	v_mad_i64_i32 v[16:17], s[0:1], v14, s89, v[16:17]
	v_ashrrev_i32_e32 v3, 31, v2
	v_lshl_add_u64 v[16:17], v[2:3], 2, v[16:17]
	v_lshl_add_u64 v[56:57], v[16:17], 0, v[0:1]
	v_add_co_u32_e64 v16, s[0:1], s43, v56
	global_load_dword v54, v[56:57], off nt
	s_nop 0
	v_addc_co_u32_e64 v17, s[0:1], 0, v57, s[0:1]
	global_load_dword v49, v[16:17], off nt
	v_add_co_u32_e64 v16, s[0:1], s75, v56
	v_ashrrev_i32_e32 v15, 31, v14
	s_nop 0
	v_addc_co_u32_e64 v17, s[0:1], 0, v57, s[0:1]
	global_load_dword v48, v[16:17], off nt
	v_add_co_u32_e64 v16, s[0:1], s44, v56
	v_add_u32_e32 v21, s52, v21
	s_nop 0
	v_addc_co_u32_e64 v17, s[0:1], 0, v57, s[0:1]
	global_load_dword v47, v[16:17], off nt
	v_add_co_u32_e64 v16, s[0:1], s91, v56
	v_add_u32_e32 v12, s3, v12
	s_nop 0
	v_addc_co_u32_e64 v17, s[0:1], 0, v57, s[0:1]
	global_load_dword v45, v[16:17], off nt
	v_add_co_u32_e64 v16, s[0:1], s45, v56
	s_nop 1
	v_addc_co_u32_e64 v17, s[0:1], 0, v57, s[0:1]
	global_load_dword v44, v[16:17], off nt
	v_add_co_u32_e64 v16, s[0:1], s74, v56
	s_nop 1
	v_addc_co_u32_e64 v17, s[0:1], 0, v57, s[0:1]
	global_load_dword v43, v[16:17], off nt
	v_add_co_u32_e64 v16, s[0:1], s46, v56
	s_nop 1
	v_addc_co_u32_e64 v17, s[0:1], 0, v57, s[0:1]
	global_load_dword v42, v[16:17], off nt
	v_add_co_u32_e64 v16, s[0:1], s93, v56
	s_nop 1
	v_addc_co_u32_e64 v17, s[0:1], 0, v57, s[0:1]
	global_load_dword v41, v[16:17], off nt
	v_add_co_u32_e64 v16, s[0:1], s47, v56
	s_nop 1
	v_addc_co_u32_e64 v17, s[0:1], 0, v57, s[0:1]
	global_load_dword v40, v[16:17], off nt
	v_add_co_u32_e64 v16, s[0:1], s72, v56
	s_nop 1
	v_addc_co_u32_e64 v17, s[0:1], 0, v57, s[0:1]
	global_load_dword v39, v[16:17], off nt
	v_add_co_u32_e64 v16, s[0:1], s48, v56
	s_nop 1
	v_addc_co_u32_e64 v17, s[0:1], 0, v57, s[0:1]
	global_load_dword v38, v[16:17], off nt
	v_add_co_u32_e64 v16, s[0:1], s95, v56
	s_nop 1
	v_addc_co_u32_e64 v17, s[0:1], 0, v57, s[0:1]
	global_load_dword v37, v[16:17], off nt
	v_add_co_u32_e64 v16, s[0:1], s53, v56
	s_nop 1
	v_addc_co_u32_e64 v17, s[0:1], 0, v57, s[0:1]
	global_load_dword v36, v[16:17], off nt
	v_add_co_u32_e64 v16, s[0:1], s54, v56
	s_nop 1
	v_addc_co_u32_e64 v17, s[0:1], 0, v57, s[0:1]
	global_load_dword v35, v[16:17], off nt
	v_add_co_u32_e64 v16, s[0:1], s61, v56
	s_nop 1
	v_addc_co_u32_e64 v17, s[0:1], 0, v57, s[0:1]
	global_load_dword v34, v[16:17], off nt
	v_add_co_u32_e64 v16, s[0:1], s83, v56
	s_nop 1
	v_addc_co_u32_e64 v17, s[0:1], 0, v57, s[0:1]
	global_load_dword v33, v[16:17], off nt
	v_add_co_u32_e64 v16, s[0:1], s66, v56
	s_nop 1
	v_addc_co_u32_e64 v17, s[0:1], 0, v57, s[0:1]
	global_load_dword v32, v[16:17], off nt
	v_add_co_u32_e64 v16, s[0:1], s67, v56
	s_nop 1
	v_addc_co_u32_e64 v17, s[0:1], 0, v57, s[0:1]
	global_load_dword v31, v[16:17], off nt
	v_add_co_u32_e64 v16, s[0:1], s71, v56
	s_nop 1
	v_addc_co_u32_e64 v17, s[0:1], 0, v57, s[0:1]
	global_load_dword v30, v[16:17], off nt
	v_add_co_u32_e64 v16, s[0:1], s33, v56
	s_nop 1
	v_addc_co_u32_e64 v17, s[0:1], 0, v57, s[0:1]
	global_load_dword v29, v[16:17], off nt
	v_add_co_u32_e64 v16, s[0:1], s78, v56
	s_nop 1
	v_addc_co_u32_e64 v17, s[0:1], 0, v57, s[0:1]
	global_load_dword v28, v[16:17], off nt
	v_add_co_u32_e64 v16, s[0:1], s79, v56
	s_nop 1
	v_addc_co_u32_e64 v17, s[0:1], 0, v57, s[0:1]
	global_load_dword v27, v[16:17], off nt
	v_add_co_u32_e64 v16, s[0:1], s82, v56
	s_nop 1
	v_addc_co_u32_e64 v17, s[0:1], 0, v57, s[0:1]
	global_load_dword v26, v[16:17], off nt
	v_add_co_u32_e64 v16, s[0:1], s80, v56
	s_nop 1
	v_addc_co_u32_e64 v17, s[0:1], 0, v57, s[0:1]
	global_load_dword v25, v[16:17], off nt
	v_add_co_u32_e64 v16, s[0:1], s90, v56
	s_nop 1
	v_addc_co_u32_e64 v17, s[0:1], 0, v57, s[0:1]
	global_load_dword v24, v[16:17], off nt
	v_add_co_u32_e64 v16, s[0:1], s7, v56
	s_nop 1
	v_addc_co_u32_e64 v17, s[0:1], 0, v57, s[0:1]
	global_load_dword v23, v[16:17], off nt
	v_add_co_u32_e64 v16, s[0:1], s92, v56
	s_nop 1
	v_addc_co_u32_e64 v17, s[0:1], 0, v57, s[0:1]
	global_load_dword v22, v[16:17], off nt
	v_add_co_u32_e64 v16, s[0:1], s97, v56
	s_nop 1
	v_addc_co_u32_e64 v17, s[0:1], 0, v57, s[0:1]
	v_add_co_u32_e64 v58, s[0:1], s73, v56
	global_load_dword v17, v[16:17], off nt
	s_nop 0
	v_addc_co_u32_e64 v59, s[0:1], 0, v57, s[0:1]
	global_load_dword v16, v[58:59], off nt
	v_add_co_u32_e64 v58, s[0:1], s76, v56
	s_nop 1
	v_addc_co_u32_e64 v59, s[0:1], 0, v57, s[0:1]
	v_add_co_u32_e64 v56, s[0:1], s77, v56
	global_load_dword v5, v[58:59], off nt
	s_nop 0
	v_addc_co_u32_e64 v57, s[0:1], 0, v57, s[0:1]
	global_load_dword v3, v[56:57], off nt
	v_lshl_add_u64 v[56:57], v[14:15], 2, s[30:31]
	global_load_dword v96, v[56:57], off
	global_load_dword v97, v[56:57], off offset:8
	global_load_dword v98, v[56:57], off offset:16
	global_load_dword v99, v[56:57], off offset:24
	global_load_dword v100, v[56:57], off offset:32
	global_load_dword v101, v[56:57], off offset:40
	global_load_dword v102, v[56:57], off offset:48
	global_load_dword v103, v[56:57], off offset:56
	global_load_dword v104, v[56:57], off offset:64
	global_load_dword v105, v[56:57], off offset:72
	global_load_dword v106, v[56:57], off offset:80
	global_load_dword v107, v[56:57], off offset:88
	global_load_dword v108, v[56:57], off offset:96
	global_load_dword v109, v[56:57], off offset:104
	global_load_dword v110, v[56:57], off offset:112
	global_load_dword v111, v[56:57], off offset:120
	global_load_dword v112, v[56:57], off offset:128
	global_load_dword v113, v[56:57], off offset:136
	global_load_dword v114, v[56:57], off offset:144
	global_load_dword v115, v[56:57], off offset:152
	global_load_dword v116, v[56:57], off offset:160
	global_load_dword v117, v[56:57], off offset:168
	global_load_dword v118, v[56:57], off offset:176
	global_load_dword v119, v[56:57], off offset:184
	global_load_dword v120, v[56:57], off offset:192
	global_load_dword v121, v[56:57], off offset:200
	global_load_dword v122, v[56:57], off offset:208
	global_load_dword v123, v[56:57], off offset:216
	global_load_dword v124, v[56:57], off offset:224
	global_load_dword v125, v[56:57], off offset:232
	global_load_dword v126, v[56:57], off offset:240
	global_load_dword v127, v[56:57], off offset:248
	v_cmp_lt_i32_e64 s[0:1], s36, v21
	s_or_b64 s[38:39], s[0:1], s[38:39]
	s_waitcnt vmcnt(0) lgkmcnt(0)
	v_mov_b32_e32 v14, v96
	v_mov_b32_e32 v15, v101
	v_mul_f32_e32 v54, v54, v14
	v_mul_f32_e32 v15, v44, v15
	v_mov_b32_e32 v14, v97
	v_mov_b32_e32 v44, v102
	v_mul_f32_e32 v49, v49, v14
	v_mul_f32_e32 v43, v43, v44
	v_mov_b32_e32 v14, v98
	v_mov_b32_e32 v44, v103
	v_mul_f32_e32 v48, v48, v14
	v_mul_f32_e32 v42, v42, v44
	v_mov_b32_e32 v14, v99
	v_mov_b32_e32 v44, v104
	v_mul_f32_e32 v47, v47, v14
	v_mul_f32_e32 v41, v41, v44
	v_mov_b32_e32 v14, v100
	v_mov_b32_e32 v44, v105
	v_mul_f32_e32 v14, v45, v14
	v_mul_f32_e32 v40, v40, v44
	v_mov_b32_e32 v44, v106
	v_mul_f32_e32 v39, v39, v44
	v_mov_b32_e32 v44, v107
	v_mul_f32_e32 v38, v38, v44
	v_mov_b32_e32 v44, v108
	v_mul_f32_e32 v37, v37, v44
	v_mov_b32_e32 v44, v109
	v_mul_f32_e32 v36, v36, v44
	v_mov_b32_e32 v44, v110
	v_mul_f32_e32 v35, v35, v44
	v_mov_b32_e32 v44, v111
	v_mul_f32_e32 v34, v34, v44
	v_mov_b32_e32 v44, v112
	v_mul_f32_e32 v33, v33, v44
	v_mov_b32_e32 v44, v113
	v_mul_f32_e32 v32, v32, v44
	v_mov_b32_e32 v44, v114
	v_mul_f32_e32 v31, v31, v44
	v_mov_b32_e32 v44, v115
	v_mul_f32_e32 v30, v30, v44
	v_mov_b32_e32 v44, v116
	v_mul_f32_e32 v29, v29, v44
	v_mov_b32_e32 v44, v117
	v_mul_f32_e32 v28, v28, v44
	v_mov_b32_e32 v44, v118
	v_mul_f32_e32 v27, v27, v44
	v_mov_b32_e32 v44, v119
	v_mul_f32_e32 v26, v26, v44
	v_mov_b32_e32 v44, v120
	v_mul_f32_e32 v25, v25, v44
	v_mov_b32_e32 v44, v121
	v_mul_f32_e32 v24, v24, v44
	v_mov_b32_e32 v44, v122
	v_mul_f32_e32 v23, v23, v44
	v_mov_b32_e32 v44, v123
	v_mul_f32_e32 v22, v22, v44
	v_mov_b32_e32 v44, v124
	v_mul_f32_e32 v17, v17, v44
	v_mov_b32_e32 v44, v125
	v_mul_f32_e32 v16, v16, v44
	v_mov_b32_e32 v44, v126
	v_mul_f32_e32 v5, v5, v44
	ds_write2_b32 v20, v54, v49 offset1:66
	ds_write2_b32 v20, v48, v47 offset0:132 offset1:198
	v_mov_b32_e32 v44, v127
	v_mul_f32_e32 v3, v3, v44
	v_add_u32_e32 v44, 0x400, v20
	ds_write2_b32 v44, v14, v15 offset0:8 offset1:74
	ds_write2_b32 v44, v43, v42 offset0:140 offset1:206
	v_add_u32_e32 v14, 0x800, v20
	ds_write2_b32 v14, v41, v40 offset0:16 offset1:82
	ds_write2_b32 v14, v39, v38 offset0:148 offset1:214
	v_add_u32_e32 v14, 0xc00, v20
	ds_write2_b32 v14, v37, v36 offset0:24 offset1:90
	ds_write2_b32 v14, v35, v34 offset0:156 offset1:222
	v_add_u32_e32 v14, 0x1000, v20
	ds_write2_b32 v14, v33, v32 offset0:32 offset1:98
	ds_write2_b32 v14, v31, v30 offset0:164 offset1:230
	v_add_u32_e32 v14, 0x1400, v20
	ds_write2_b32 v14, v29, v28 offset0:40 offset1:106
	ds_write2_b32 v14, v27, v26 offset0:172 offset1:238
	v_add_u32_e32 v14, 0x1800, v20
	ds_write2_b32 v14, v25, v24 offset0:48 offset1:114
	ds_write2_b32 v14, v23, v22 offset0:180 offset1:246
	v_add_u32_e32 v14, 0x1c00, v20
	ds_write2_b32 v14, v17, v16 offset0:56 offset1:122
	ds_write2_b32 v14, v5, v3 offset0:188 offset1:254
	v_add_u32_e32 v26, v2, v18
	s_waitcnt lgkmcnt(0)
	v_ashrrev_i32_e32 v5, 31, v4
	v_add_u32_e32 v2, 0x300, v26
	v_lshl_add_u64 v[14:15], v[4:5], 1, v[10:11]
	ds_read2_b32 v[4:5], v19 offset1:33
	v_ashrrev_i32_e32 v3, 31, v2
	s_waitcnt lgkmcnt(0)
	v_cvt_pk_bf16_f32 v22, v4, v5
	ds_read2_b32 v[4:5], v19 offset0:66 offset1:99
	v_lshlrev_b64 v[2:3], 12, v[2:3]
	s_waitcnt lgkmcnt(0)
	v_cvt_pk_bf16_f32 v23, v4, v5
	ds_read2_b32 v[4:5], v19 offset0:132 offset1:165
	v_lshl_add_u64 v[2:3], v[14:15], 0, v[2:3]
	s_waitcnt lgkmcnt(0)
	v_cvt_pk_bf16_f32 v24, v4, v5
	ds_read2_b32 v[4:5], v19 offset0:198 offset1:231
	s_waitcnt lgkmcnt(0)
	v_cvt_pk_bf16_f32 v25, v4, v5
	global_store_dwordx4 v[2:3], v[22:25], off
	ds_read2_b32 v[2:3], v19 offset0:8 offset1:41
	s_waitcnt lgkmcnt(0)
	v_cvt_pk_bf16_f32 v2, v2, v3
	ds_read2_b32 v[4:5], v19 offset0:74 offset1:107
	s_waitcnt lgkmcnt(0)
	v_cvt_pk_bf16_f32 v3, v4, v5
	ds_read2_b32 v[4:5], v19 offset0:140 offset1:173
	s_waitcnt lgkmcnt(0)
	v_cvt_pk_bf16_f32 v4, v4, v5
	ds_read2_b32 v[16:17], v19 offset0:206 offset1:239
	s_waitcnt lgkmcnt(0)
	v_cvt_pk_bf16_f32 v5, v16, v17
	v_add_u32_e32 v16, 0x308, v26
	v_ashrrev_i32_e32 v17, 31, v16
	v_lshlrev_b64 v[16:17], 12, v[16:17]
	v_lshl_add_u64 v[16:17], v[14:15], 0, v[16:17]
	global_store_dwordx4 v[16:17], v[2:5], off
	ds_read2_b32 v[2:3], v19 offset0:16 offset1:49
	s_waitcnt lgkmcnt(0)
	v_cvt_pk_bf16_f32 v2, v2, v3
	ds_read2_b32 v[4:5], v19 offset0:82 offset1:115
	s_waitcnt lgkmcnt(0)
	v_cvt_pk_bf16_f32 v3, v4, v5
	ds_read2_b32 v[4:5], v19 offset0:148 offset1:181
	s_waitcnt lgkmcnt(0)
	v_cvt_pk_bf16_f32 v4, v4, v5
	ds_read2_b32 v[16:17], v19 offset0:214 offset1:247
	s_waitcnt lgkmcnt(0)
	v_cvt_pk_bf16_f32 v5, v16, v17
	v_add_u32_e32 v16, 0x310, v26
	v_ashrrev_i32_e32 v17, 31, v16
	v_lshlrev_b64 v[16:17], 12, v[16:17]
	v_lshl_add_u64 v[16:17], v[14:15], 0, v[16:17]
	global_store_dwordx4 v[16:17], v[2:5], off
	ds_read2_b32 v[2:3], v19 offset0:24 offset1:57
	s_waitcnt lgkmcnt(0)
	v_cvt_pk_bf16_f32 v2, v2, v3
	ds_read2_b32 v[4:5], v19 offset0:90 offset1:123
	s_waitcnt lgkmcnt(0)
	v_cvt_pk_bf16_f32 v3, v4, v5
	ds_read2_b32 v[4:5], v19 offset0:156 offset1:189
	s_waitcnt lgkmcnt(0)
	v_cvt_pk_bf16_f32 v4, v4, v5
	ds_read2_b32 v[16:17], v19 offset0:222 offset1:255
	s_waitcnt lgkmcnt(0)
	v_cvt_pk_bf16_f32 v5, v16, v17
	v_add_u32_e32 v16, 0x318, v26
	v_ashrrev_i32_e32 v17, 31, v16
	v_lshlrev_b64 v[16:17], 12, v[16:17]
	v_lshl_add_u64 v[14:15], v[14:15], 0, v[16:17]
	global_store_dwordx4 v[14:15], v[2:5], off
	s_waitcnt lgkmcnt(0)
	s_andn2_b64 exec, exec, s[38:39]
	s_cbranch_execnz .LBB0_915

.LBB0_918:
	v_mul_hi_i32 v2, v23, s81
	v_lshrrev_b32_e32 v3, 31, v2
	v_ashrrev_i32_e32 v2, 3, v2
	v_add_u32_e32 v2, v2, v3
	v_lshlrev_b32_e32 v4, 6, v2
	v_mad_u64_u32 v[2:3], s[6:7], v2, s49, v[12:13]
	v_or_b32_e32 v14, v4, v13
	v_mov_b64_e32 v[16:17], s[12:13]
	v_mad_i64_i32 v[16:17], s[6:7], v14, s89, v[16:17]
	v_ashrrev_i32_e32 v3, 31, v2
	v_lshl_add_u64 v[16:17], v[2:3], 2, v[16:17]
	v_lshl_add_u64 v[56:57], v[16:17], 0, v[0:1]
	v_add_co_u32_e32 v16, vcc, s43, v56
	global_load_dword v54, v[56:57], off nt
	s_nop 0
	v_addc_co_u32_e32 v17, vcc, 0, v57, vcc
	global_load_dword v49, v[16:17], off nt
	v_add_co_u32_e32 v16, vcc, s75, v56
	v_ashrrev_i32_e32 v15, 31, v14
	s_nop 0
	v_addc_co_u32_e32 v17, vcc, 0, v57, vcc
	global_load_dword v48, v[16:17], off nt
	v_add_co_u32_e32 v16, vcc, s44, v56
	v_add_u32_e32 v23, s52, v23
	s_nop 0
	v_addc_co_u32_e32 v17, vcc, 0, v57, vcc
	global_load_dword v47, v[16:17], off nt
	v_add_co_u32_e32 v16, vcc, s91, v56
	v_add_u32_e32 v12, s3, v12
	s_nop 0
	v_addc_co_u32_e32 v17, vcc, 0, v57, vcc
	global_load_dword v45, v[16:17], off nt
	v_add_co_u32_e32 v16, vcc, s45, v56
	s_nop 1
	v_addc_co_u32_e32 v17, vcc, 0, v57, vcc
	global_load_dword v44, v[16:17], off nt
	v_add_co_u32_e32 v16, vcc, s74, v56
	s_nop 1
	v_addc_co_u32_e32 v17, vcc, 0, v57, vcc
	global_load_dword v43, v[16:17], off nt
	v_add_co_u32_e32 v16, vcc, s46, v56
	s_nop 1
	v_addc_co_u32_e32 v17, vcc, 0, v57, vcc
	global_load_dword v42, v[16:17], off nt
	v_add_co_u32_e32 v16, vcc, s93, v56
	s_nop 1
	v_addc_co_u32_e32 v17, vcc, 0, v57, vcc
	global_load_dword v41, v[16:17], off nt
	v_add_co_u32_e32 v16, vcc, s47, v56
	s_nop 1
	v_addc_co_u32_e32 v17, vcc, 0, v57, vcc
	global_load_dword v40, v[16:17], off nt
	v_add_co_u32_e32 v16, vcc, s72, v56
	s_nop 1
	v_addc_co_u32_e32 v17, vcc, 0, v57, vcc
	global_load_dword v39, v[16:17], off nt
	v_add_co_u32_e32 v16, vcc, s48, v56
	s_nop 1
	v_addc_co_u32_e32 v17, vcc, 0, v57, vcc
	global_load_dword v38, v[16:17], off nt
	v_add_co_u32_e32 v16, vcc, s95, v56
	s_nop 1
	v_addc_co_u32_e32 v17, vcc, 0, v57, vcc
	global_load_dword v37, v[16:17], off nt
	v_add_co_u32_e32 v16, vcc, s53, v56
	s_nop 1
	v_addc_co_u32_e32 v17, vcc, 0, v57, vcc
	global_load_dword v36, v[16:17], off nt
	v_add_co_u32_e32 v16, vcc, s54, v56
	s_nop 1
	v_addc_co_u32_e32 v17, vcc, 0, v57, vcc
	global_load_dword v35, v[16:17], off nt
	v_add_co_u32_e32 v16, vcc, s61, v56
	s_nop 1
	v_addc_co_u32_e32 v17, vcc, 0, v57, vcc
	global_load_dword v34, v[16:17], off nt
	v_add_co_u32_e32 v16, vcc, s83, v56
	s_nop 1
	v_addc_co_u32_e32 v17, vcc, 0, v57, vcc
	global_load_dword v33, v[16:17], off nt
	v_add_co_u32_e32 v16, vcc, s66, v56
	s_nop 1
	v_addc_co_u32_e32 v17, vcc, 0, v57, vcc
	global_load_dword v32, v[16:17], off nt
	v_add_co_u32_e32 v16, vcc, s67, v56
	s_nop 1
	v_addc_co_u32_e32 v17, vcc, 0, v57, vcc
	global_load_dword v31, v[16:17], off nt
	v_add_co_u32_e32 v16, vcc, s71, v56
	s_nop 1
	v_addc_co_u32_e32 v17, vcc, 0, v57, vcc
	global_load_dword v30, v[16:17], off nt
	v_add_co_u32_e32 v16, vcc, s33, v56
	s_nop 1
	v_addc_co_u32_e32 v17, vcc, 0, v57, vcc
	global_load_dword v29, v[16:17], off nt
	v_add_co_u32_e32 v16, vcc, s78, v56
	s_nop 1
	v_addc_co_u32_e32 v17, vcc, 0, v57, vcc
	global_load_dword v28, v[16:17], off nt
	v_add_co_u32_e32 v16, vcc, s79, v56
	s_nop 1
	v_addc_co_u32_e32 v17, vcc, 0, v57, vcc
	global_load_dword v27, v[16:17], off nt
	v_add_co_u32_e32 v16, vcc, s82, v56
	s_nop 1
	v_addc_co_u32_e32 v17, vcc, 0, v57, vcc
	global_load_dword v26, v[16:17], off nt
	v_add_co_u32_e32 v16, vcc, s80, v56
	s_nop 1
	v_addc_co_u32_e32 v17, vcc, 0, v57, vcc
	global_load_dword v25, v[16:17], off nt
	v_add_co_u32_e32 v16, vcc, s90, v56
	s_nop 1
	v_addc_co_u32_e32 v17, vcc, 0, v57, vcc
	global_load_dword v24, v[16:17], off nt
	v_add_co_u32_e32 v16, vcc, s11, v56
	s_nop 1
	v_addc_co_u32_e32 v17, vcc, 0, v57, vcc
	global_load_dword v19, v[16:17], off nt
	v_add_co_u32_e32 v16, vcc, s18, v56
	s_nop 1
	v_addc_co_u32_e32 v17, vcc, 0, v57, vcc
	global_load_dword v18, v[16:17], off nt
	v_add_co_u32_e32 v16, vcc, s97, v56
	s_nop 1
	v_addc_co_u32_e32 v17, vcc, 0, v57, vcc
	v_add_co_u32_e32 v58, vcc, s19, v56
	global_load_dword v17, v[16:17], off nt
	s_nop 0
	v_addc_co_u32_e32 v59, vcc, 0, v57, vcc
	global_load_dword v16, v[58:59], off nt
	v_add_co_u32_e32 v58, vcc, s73, v56
	s_nop 1
	v_addc_co_u32_e32 v59, vcc, 0, v57, vcc
	v_add_co_u32_e32 v56, vcc, s77, v56
	global_load_dword v5, v[58:59], off nt
	s_nop 0
	v_addc_co_u32_e32 v57, vcc, 0, v57, vcc
	global_load_dword v3, v[56:57], off nt
	v_lshl_add_u64 v[56:57], v[14:15], 2, s[14:15]
	global_load_dword v96, v[56:57], off
	global_load_dword v97, v[56:57], off offset:8
	global_load_dword v98, v[56:57], off offset:16
	global_load_dword v99, v[56:57], off offset:24
	global_load_dword v100, v[56:57], off offset:32
	global_load_dword v101, v[56:57], off offset:40
	global_load_dword v102, v[56:57], off offset:48
	global_load_dword v103, v[56:57], off offset:56
	global_load_dword v104, v[56:57], off offset:64
	global_load_dword v105, v[56:57], off offset:72
	global_load_dword v106, v[56:57], off offset:80
	global_load_dword v107, v[56:57], off offset:88
	global_load_dword v108, v[56:57], off offset:96
	global_load_dword v109, v[56:57], off offset:104
	global_load_dword v110, v[56:57], off offset:112
	global_load_dword v111, v[56:57], off offset:120
	global_load_dword v112, v[56:57], off offset:128
	global_load_dword v113, v[56:57], off offset:136
	global_load_dword v114, v[56:57], off offset:144
	global_load_dword v115, v[56:57], off offset:152
	global_load_dword v116, v[56:57], off offset:160
	global_load_dword v117, v[56:57], off offset:168
	global_load_dword v118, v[56:57], off offset:176
	global_load_dword v119, v[56:57], off offset:184
	global_load_dword v120, v[56:57], off offset:192
	global_load_dword v121, v[56:57], off offset:200
	global_load_dword v122, v[56:57], off offset:208
	global_load_dword v123, v[56:57], off offset:216
	global_load_dword v124, v[56:57], off offset:224
	global_load_dword v125, v[56:57], off offset:232
	global_load_dword v126, v[56:57], off offset:240
	global_load_dword v127, v[56:57], off offset:248
	v_cmp_lt_i32_e32 vcc, s30, v23
	s_or_b64 s[16:17], vcc, s[16:17]
	s_waitcnt vmcnt(0) lgkmcnt(0)
	v_mov_b32_e32 v14, v96
	v_mov_b32_e32 v15, v101
	v_mul_f32_e32 v54, v54, v14
	v_mul_f32_e32 v15, v44, v15
	v_mov_b32_e32 v14, v97
	v_mov_b32_e32 v44, v102
	v_mul_f32_e32 v49, v49, v14
	v_mul_f32_e32 v43, v43, v44
	v_mov_b32_e32 v14, v98
	v_mov_b32_e32 v44, v103
	v_mul_f32_e32 v48, v48, v14
	v_mul_f32_e32 v42, v42, v44
	v_mov_b32_e32 v14, v99
	v_mov_b32_e32 v44, v104
	v_mul_f32_e32 v47, v47, v14
	v_mul_f32_e32 v41, v41, v44
	v_mov_b32_e32 v14, v100
	v_mov_b32_e32 v44, v105
	v_mul_f32_e32 v14, v45, v14
	v_mul_f32_e32 v40, v40, v44
	v_mov_b32_e32 v44, v106
	v_mul_f32_e32 v39, v39, v44
	v_mov_b32_e32 v44, v107
	v_mul_f32_e32 v38, v38, v44
	v_mov_b32_e32 v44, v108
	v_mul_f32_e32 v37, v37, v44
	v_mov_b32_e32 v44, v109
	v_mul_f32_e32 v36, v36, v44
	v_mov_b32_e32 v44, v110
	v_mul_f32_e32 v35, v35, v44
	v_mov_b32_e32 v44, v111
	v_mul_f32_e32 v34, v34, v44
	v_mov_b32_e32 v44, v112
	v_mul_f32_e32 v33, v33, v44
	v_mov_b32_e32 v44, v113
	v_mul_f32_e32 v32, v32, v44
	v_mov_b32_e32 v44, v114
	v_mul_f32_e32 v31, v31, v44
	v_mov_b32_e32 v44, v115
	v_mul_f32_e32 v30, v30, v44
	v_mov_b32_e32 v44, v116
	v_mul_f32_e32 v29, v29, v44
	v_mov_b32_e32 v44, v117
	v_mul_f32_e32 v28, v28, v44
	v_mov_b32_e32 v44, v118
	v_mul_f32_e32 v27, v27, v44
	v_mov_b32_e32 v44, v119
	v_mul_f32_e32 v26, v26, v44
	v_mov_b32_e32 v44, v120
	v_mul_f32_e32 v25, v25, v44
	v_mov_b32_e32 v44, v121
	v_mul_f32_e32 v24, v24, v44
	v_mov_b32_e32 v44, v122
	v_mul_f32_e32 v19, v19, v44
	v_mov_b32_e32 v44, v123
	v_mul_f32_e32 v18, v18, v44
	v_mov_b32_e32 v44, v124
	v_mul_f32_e32 v17, v17, v44
	v_mov_b32_e32 v44, v125
	v_mul_f32_e32 v16, v16, v44
	v_mov_b32_e32 v44, v126
	v_mul_f32_e32 v5, v5, v44
	ds_write2_b32 v22, v54, v49 offset1:66
	ds_write2_b32 v22, v48, v47 offset0:132 offset1:198
	v_mov_b32_e32 v44, v127
	v_mul_f32_e32 v3, v3, v44
	v_add_u32_e32 v44, 0x400, v22
	ds_write2_b32 v44, v14, v15 offset0:8 offset1:74
	ds_write2_b32 v44, v43, v42 offset0:140 offset1:206
	v_add_u32_e32 v14, 0x800, v22
	ds_write2_b32 v14, v41, v40 offset0:16 offset1:82
	ds_write2_b32 v14, v39, v38 offset0:148 offset1:214
	v_add_u32_e32 v14, 0xc00, v22
	ds_write2_b32 v14, v37, v36 offset0:24 offset1:90
	ds_write2_b32 v14, v35, v34 offset0:156 offset1:222
	v_add_u32_e32 v14, 0x1000, v22
	ds_write2_b32 v14, v33, v32 offset0:32 offset1:98
	ds_write2_b32 v14, v31, v30 offset0:164 offset1:230
	v_add_u32_e32 v14, 0x1400, v22
	ds_write2_b32 v14, v29, v28 offset0:40 offset1:106
	ds_write2_b32 v14, v27, v26 offset0:172 offset1:238
	v_add_u32_e32 v14, 0x1800, v22
	ds_write2_b32 v14, v25, v24 offset0:48 offset1:114
	ds_write2_b32 v14, v19, v18 offset0:180 offset1:246
	v_add_u32_e32 v14, 0x1c00, v22
	ds_write2_b32 v14, v17, v16 offset0:56 offset1:122
	ds_write2_b32 v14, v5, v3 offset0:188 offset1:254
	s_waitcnt lgkmcnt(0)
	v_ashrrev_i32_e32 v5, 31, v4
	v_add_u32_e32 v16, v2, v20
	v_lshl_add_u64 v[14:15], v[4:5], 1, v[10:11]
	ds_read2_b32 v[4:5], v21 offset1:33
	v_ashrrev_i32_e32 v17, 31, v16
	s_waitcnt lgkmcnt(0)
	v_cvt_pk_bf16_f32 v24, v4, v5
	ds_read2_b32 v[4:5], v21 offset0:66 offset1:99
	v_lshlrev_b64 v[2:3], 12, v[16:17]
	s_waitcnt lgkmcnt(0)
	v_cvt_pk_bf16_f32 v25, v4, v5
	ds_read2_b32 v[4:5], v21 offset0:132 offset1:165
	v_lshl_add_u64 v[2:3], v[14:15], 0, v[2:3]
	s_waitcnt lgkmcnt(0)
	v_cvt_pk_bf16_f32 v26, v4, v5
	ds_read2_b32 v[4:5], v21 offset0:198 offset1:231
	s_waitcnt lgkmcnt(0)
	v_cvt_pk_bf16_f32 v27, v4, v5
	global_store_dwordx4 v[2:3], v[24:27], off
	ds_read2_b32 v[2:3], v21 offset0:8 offset1:41
	s_waitcnt lgkmcnt(0)
	v_cvt_pk_bf16_f32 v2, v2, v3
	ds_read2_b32 v[4:5], v21 offset0:74 offset1:107
	s_waitcnt lgkmcnt(0)
	v_cvt_pk_bf16_f32 v3, v4, v5
	ds_read2_b32 v[4:5], v21 offset0:140 offset1:173
	s_waitcnt lgkmcnt(0)
	v_cvt_pk_bf16_f32 v4, v4, v5
	ds_read2_b32 v[18:19], v21 offset0:206 offset1:239
	s_waitcnt lgkmcnt(0)
	v_cvt_pk_bf16_f32 v5, v18, v19
	v_add_u32_e32 v18, 8, v16
	v_ashrrev_i32_e32 v19, 31, v18
	v_lshlrev_b64 v[18:19], 12, v[18:19]
	v_lshl_add_u64 v[18:19], v[14:15], 0, v[18:19]
	global_store_dwordx4 v[18:19], v[2:5], off
	ds_read2_b32 v[2:3], v21 offset0:16 offset1:49
	s_waitcnt lgkmcnt(0)
	v_cvt_pk_bf16_f32 v2, v2, v3
	ds_read2_b32 v[4:5], v21 offset0:82 offset1:115
	s_waitcnt lgkmcnt(0)
	v_cvt_pk_bf16_f32 v3, v4, v5
	ds_read2_b32 v[4:5], v21 offset0:148 offset1:181
	s_waitcnt lgkmcnt(0)
	v_cvt_pk_bf16_f32 v4, v4, v5
	ds_read2_b32 v[18:19], v21 offset0:214 offset1:247
	s_waitcnt lgkmcnt(0)
	v_cvt_pk_bf16_f32 v5, v18, v19
	v_add_u32_e32 v18, 16, v16
	v_ashrrev_i32_e32 v19, 31, v18
	v_lshlrev_b64 v[18:19], 12, v[18:19]
	v_lshl_add_u64 v[18:19], v[14:15], 0, v[18:19]
	global_store_dwordx4 v[18:19], v[2:5], off
	v_add_u32_e32 v16, 24, v16
	ds_read2_b32 v[2:3], v21 offset0:24 offset1:57
	v_ashrrev_i32_e32 v17, 31, v16
	s_waitcnt lgkmcnt(0)
	v_cvt_pk_bf16_f32 v2, v2, v3
	ds_read2_b32 v[4:5], v21 offset0:90 offset1:123
	v_lshlrev_b64 v[16:17], 12, v[16:17]
	s_waitcnt lgkmcnt(0)
	v_cvt_pk_bf16_f32 v3, v4, v5
	ds_read2_b32 v[4:5], v21 offset0:156 offset1:189
	v_lshl_add_u64 v[14:15], v[14:15], 0, v[16:17]
	s_waitcnt lgkmcnt(0)
	v_cvt_pk_bf16_f32 v4, v4, v5
	ds_read2_b32 v[18:19], v21 offset0:222 offset1:255
	s_waitcnt lgkmcnt(0)
	v_cvt_pk_bf16_f32 v5, v18, v19
	global_store_dwordx4 v[14:15], v[2:5], off
	s_waitcnt lgkmcnt(0)
	s_andn2_b64 exec, exec, s[16:17]
	s_cbranch_execnz .LBB0_918
